# as v94 plus the wkv weight conversion also moved to the 32 free workgroups of the GEMM1 phase
# speedup vs baseline: 1.0122x; 1.0002x over previous
_Z10fwd_kernel4Args:
	s_mov_b32 s94, s2
	s_load_dwordx8 s[76:83], s[0:1], 0x80
	s_load_dword s2, s[0:1], 0xb8
	s_load_dwordx4 s[84:87], s[0:1], 0xa0
	s_load_dwordx2 s[88:89], s[0:1], 0xb0
	s_add_u32 s58, s0, 0xb0
	v_and_b32_e32 v165, 0x3ff, v0
	s_addc_u32 s59, s1, 0
	v_cmp_gt_u32_e32 vcc, 2, v165
	s_waitcnt lgkmcnt(0)
	v_writelane_b32 v228, s2, 0
	s_mov_b32 s101, 0
	s_mov_b32 s100, 0
	s_movk_i32 s99, 0x44ff
	s_cmp_lg_u32 s88, 0x100
	s_cbranch_scc1 .Lp0_full
	s_movk_i32 s99, 0x18ff

.LBB0_154:
	s_cmp_gt_u32 s101, 1
	s_cbranch_scc1 .Lp1_conv_ret
	s_cmp_lg_u32 s101, 0
	s_cbranch_scc1 .Ltramp_back
	s_mov_b32 s24, s98
	s_cmpk_gt_i32 s24, 0x23ff
	s_cbranch_scc0 .LBB0_156
	s_branch .LBB0_162
.LBB0_155:
	v_readlane_b32 s88, v228, 6
	v_readlane_b32 s58, v228, 12
	v_readlane_b32 s94, v228, 16
	v_readlane_b32 s89, v228, 7
	v_readlane_b32 s59, v228, 13
	v_readlane_b32 s95, v228, 17
	s_cmp_gt_u32 s101, 1
	s_cbranch_scc1 .Lp1_conv_ret
	s_cmp_lg_u32 s101, 0
	s_cbranch_scc1 .Ltramp_back
	s_mov_b32 s24, s98
	s_lshl_b32 s44, s88, 3
	s_cmpk_gt_i32 s24, 0x23ff
	s_cbranch_scc1 .LBB0_162

.LBB0_248:
.LBB0_249:
	s_cmp_lt_i32 s86, 2
	s_cselect_b64 s[2:3], -1, 0
	s_add_u32 s62, s84, 0xb000000
	s_addc_u32 s63, s85, 0
	s_add_u32 s64, s84, 0xf800000
	s_addc_u32 s65, s85, 0
	s_add_u32 s70, s84, 0x13800000
	s_addc_u32 s71, s85, 0
	s_add_u32 s4, s84, 0x17800000
	s_addc_u32 s5, s85, 0
	s_and_b64 s[0:1], s[2:3], s[0:1]
	v_writelane_b32 v228, s4, 14
	s_andn2_b64 vcc, exec, s[0:1]
	s_nop 0
	v_writelane_b32 v228, s5, 15
	s_cbranch_vccnz .LBB0_392
	s_cmp_lg_u32 s88, 0x100
	s_cbranch_scc1 .Lp1_all
	s_cmp_lt_u32 s94, 224
	s_cbranch_scc1 .Lp1_gemm
	v_readlane_b32 s0, v228, 12
	v_readlane_b32 s1, v228, 13
	s_sub_u32 s0, s0, 0xb0
	s_subb_u32 s1, s1, 0
	s_load_dwordx16 s[60:75], s[0:1], 0x0
	s_load_dwordx4 s[76:79], s[0:1], 0x80
	s_add_i32 s94, s94, 160
	s_mov_b32 s101, 3
	s_movk_i32 s99, 0x39ff
	s_movk_i32 s100, 0x1900
	s_waitcnt lgkmcnt(0)
	s_branch .Lp0_entry
.Lp1_conv_ret:
	s_sub_i32 s94, s94, 160
	s_mov_b32 s101, 0
	s_add_u32 s62, s84, 0xb000000
	s_addc_u32 s63, s85, 0
	s_add_u32 s64, s84, 0xf800000
	s_addc_u32 s65, s85, 0
	s_add_u32 s70, s84, 0x13800000
	s_addc_u32 s71, s85, 0
	s_add_u32 s4, s84, 0x17800000
	s_addc_u32 s5, s85, 0
	s_nop 0
	v_writelane_b32 v228, s94, 16
	v_writelane_b32 v228, s4, 14
	v_writelane_b32 v228, s5, 15
	s_waitcnt vmcnt(0) lgkmcnt(0)
	s_barrier
	s_mov_b64 s[0:1], -1
	s_branch .LBB0_392
.Lp1_gemm:
	s_movk_i32 s88, 224
